# v104 + P2 wave-7 scan: A_log/dt_bias of the next unit prefetched with the raw rows (no exposed load+vmcnt(0) at the head of the scan)
# speedup vs baseline: 1.0112x; 1.0007x over previous
; __device__ __forceinline__ float sigmoidf_(float x) { return 1.f / (1.f + __expf(-x)); }
; __device__ __forceinline__ float softplusf_(float x) { return x > 20.f ? x : log1pf(__expf(x)); }
; #define LAS __attribute__((address_space(3)))
; template <int SKIP>
; __device__ __forceinline__ void p2_chunk_prep_fast(Frame& F, const Args& a) {
;     ...
;     LAS float* cw = (LAS float*)(F.lds + XTRA_OFF + 1024);
;     PrepRaw raw; int hcur = -1;
;     { const int lane = F.lane, fr = lane & 15, fq = lane >> 4, ib = (4 * w + fq) & 7, d8 = 8 * fr; if (u_lo < u_hi) PREP_LOAD(raw, u_lo); }
;     ...
;             if (p >= 0) { be = sigmoidf_(raw.pb); g = -__expf(A_log[h]) * softplusf_(raw.pa + dt_bias[h]); }
.LBB0_607:
	s_add_u32 s18, s26, 0xcc00000
	s_addc_u32 s19, s27, 0
	s_add_u32 s20, s26, 0x12f00000
	s_addc_u32 s21, s27, 0
	s_lshr_b32 s1, s82, 7
	s_lshl_b32 s0, s78, 2
	s_cmp_lt_i32 s84, s16
	s_cselect_b64 s[2:3], -1, 0
	s_cmp_ge_i32 s84, s16
	s_cbranch_scc1 .LBB0_609
	s_mul_hi_i32 s5, s84, 0x3e0f83e1
	s_ashr_i32 s4, s5, 3
	s_lshr_b32 s6, s5, 31
	s_add_i32 s4, s4, s6
	s_ashr_i32 s8, s4, 31
	s_lshr_b32 s8, s8, 28
	s_add_i32 s8, s4, s8
	s_and_b32 s8, s8, -16
	s_lshr_b32 s5, s5, 7
	s_mul_i32 s7, s4, 33
	s_sub_i32 s4, s4, s8
	s_lshl_b32 s90, s4, 2
	v_mov_b32_e32 v249, s90
	global_load_dword v252, v249, s[46:47]
	global_load_dword v253, v249, s[48:49]
	s_add_i32 s5, s5, s6
	s_min_u32 s6, s1, 2
	v_lshrrev_b32_e32 v1, 4, v254
	s_waitcnt vmcnt(0)
	v_lshlrev_b32_e32 v2, 3, v0
	s_lshl_b32 s6, s6, 11
	s_lshl_b32 s8, s4, 7
	v_or_b32_e32 v1, s0, v1
	v_and_b32_e32 v2, 0x78, v2
	s_sub_i32 s7, s84, s7
	s_add_i32 s8, s8, s6
	v_or_b32_e32 v2, s8, v2
	s_lshl_b32 s8, s7, 6
	v_lshlrev_b32_e32 v1, 3, v1
	v_and_or_b32 v1, v1, 56, s8
	s_lshl_b32 s5, s5, 11
	v_subrev_u32_e32 v46, 51, v1
	s_add_i32 s5, s5, -16
	v_mov_b32_e32 v47, 0x2000
	v_mov_b32_e32 v48, s5
	v_cmp_lt_i32_e32 vcc, 15, v46
	v_ashrrev_i32_e32 v3, 31, v2
	v_max_i32_e32 v4, 0, v46
	v_cndmask_b32_e32 v5, v47, v48, vcc
	v_cmp_lt_i32_e32 vcc, 14, v46
	v_lshl_add_u64 v[2:3], v[2:3], 1, s[18:19]
	v_add_u32_e32 v4, v5, v4
	s_movk_i32 s5, 0x3000
	v_max_i32_e32 v6, -1, v46
	v_cndmask_b32_e32 v7, v47, v48, vcc
	v_subrev_u32_e32 v1, 49, v1
	v_mad_i64_i32 v[4:5], s[6:7], v4, s5, v[2:3]
	v_add3_u32 v6, v6, v7, 1
	v_cmp_lt_i32_e32 vcc, 15, v1
	v_mad_i64_i32 v[6:7], s[6:7], v6, s5, v[2:3]
	global_load_dwordx4 v[30:33], v[4:5], off nt
	global_load_dwordx4 v[38:41], v[6:7], off nt
	v_max_i32_e32 v4, 0, v1
	v_cndmask_b32_e32 v1, v47, v48, vcc
	v_add_u32_e32 v1, v1, v4
	v_cmp_lt_i32_e32 vcc, 12, v46
	v_mad_i64_i32 v[4:5], s[6:7], v1, s5, v[2:3]
	v_max_i32_e32 v1, -3, v46
	v_cndmask_b32_e32 v6, v47, v48, vcc
	v_add3_u32 v1, v1, v6, 3
	v_cmp_lt_i32_e32 vcc, 11, v46
	v_mad_i64_i32 v[6:7], s[6:7], v1, s5, v[2:3]
	global_load_dwordx4 v[34:37], v[4:5], off nt
	global_load_dwordx4 v[42:45], v[6:7], off nt
	v_max_i32_e32 v1, -4, v46
	v_cndmask_b32_e32 v4, v47, v48, vcc
	v_add3_u32 v1, v1, v4, 4
	v_cmp_lt_i32_e32 vcc, 10, v46
	v_mad_i64_i32 v[4:5], s[6:7], v1, s5, v[2:3]
	v_max_i32_e32 v1, -5, v46
	v_cndmask_b32_e32 v6, v47, v48, vcc
	v_add3_u32 v1, v1, v6, 5
	v_cmp_lt_i32_e32 vcc, 9, v46
	v_mad_i64_i32 v[6:7], s[6:7], v1, s5, v[2:3]
	global_load_dwordx4 v[26:29], v[4:5], off nt
	global_load_dwordx4 v[22:25], v[6:7], off nt
	v_max_i32_e32 v1, -6, v46
	v_cndmask_b32_e32 v4, v47, v48, vcc
	v_add3_u32 v1, v1, v4, 6
	v_cmp_lt_i32_e32 vcc, 8, v46
	v_mad_i64_i32 v[4:5], s[6:7], v1, s5, v[2:3]
	v_max_i32_e32 v1, -7, v46
	v_cndmask_b32_e32 v6, v47, v48, vcc
	v_add3_u32 v1, v1, v6, 7
	v_cmp_lt_i32_e32 vcc, 7, v46
	v_mad_i64_i32 v[6:7], s[6:7], v1, s5, v[2:3]
	global_load_dwordx4 v[18:21], v[4:5], off nt
	global_load_dwordx4 v[14:17], v[6:7], off nt
	v_max_i32_e32 v1, -8, v46
	v_cndmask_b32_e32 v4, v47, v48, vcc
	v_add3_u32 v1, v1, v4, 8
	v_cmp_lt_i32_e32 vcc, 6, v46
	v_mad_i64_i32 v[4:5], s[6:7], v1, s5, v[2:3]
	v_max_i32_e32 v1, -9, v46
	v_cndmask_b32_e32 v6, v47, v48, vcc
	v_add3_u32 v1, v1, v6, 9
	v_mad_i64_i32 v[6:7], s[6:7], v1, s5, v[2:3]
	v_cmp_lt_i32_e32 vcc, 5, v46
	global_load_dwordx4 v[10:13], v[4:5], off nt
	s_nop 0
	global_load_dwordx4 v[6:9], v[6:7], off nt
	v_max_i32_e32 v1, -10, v46
	v_cndmask_b32_e32 v4, v47, v48, vcc
	v_add3_u32 v1, v1, v4, 10
	v_mad_i64_i32 v[2:3], s[6:7], v1, s5, v[2:3]
	v_or_b32_e32 v1, s8, v254
	v_subrev_u32_e32 v1, 48, v1
	v_cmp_lt_i32_e32 vcc, 15, v1
	v_max_i32_e32 v4, 0, v1
	s_ashr_i32 s5, s4, 31
	v_cndmask_b32_e32 v1, v47, v48, vcc
	v_add_u32_e32 v4, v1, v4
	v_ashrrev_i32_e32 v5, 31, v4
	v_lshlrev_b64 v[4:5], 7, v[4:5]
	v_lshl_add_u64 v[4:5], s[20:21], 0, v[4:5]
	v_lshl_add_u64 v[46:47], s[4:5], 2, v[4:5]
	global_load_dwordx4 v[2:5], v[2:3], off nt
	s_nop 0
	global_load_dword v106, v[46:47], off
	global_load_dword v81, v[46:47], off offset:64
	s_andn2_b64 vcc, exec, s[2:3]
	s_cbranch_vccz .LBB0_610
	s_branch .LBB0_724

; __device__ __forceinline__ float sigmoidf_(float x) { return 1.f / (1.f + __expf(-x)); }
; __device__ __forceinline__ float softplusf_(float x) { return x > 20.f ? x : log1pf(__expf(x)); }
; template <int SKIP>
; __device__ __forceinline__ void p2_chunk_prep_fast(Frame& F, const Args& a) {
;     ...
;         if (w == 7) {
;             const int p = p0 + lane; float be = 0.f, g = 0.f;
;             if (p >= 0) { be = sigmoidf_(raw.pb); g = -__expf(A_log[h]) * softplusf_(raw.pa + dt_bias[h]); }
; #pragma unroll
;             for (int o = 1; o < 64; o <<= 1) { const float t = __shfl_up(g, o); if (lane >= o) g += t; }
;             beta[lane] = be; gc[lane] = g;
.Lp2c_notr_10:
.LBB0_665:
	s_waitcnt vmcnt(0)
	v_subrev_u32_e32 v2, 48, v117
	s_andn2_b64 vcc, exec, s[42:43]
	s_cbranch_vccnz .LBB0_671
	v_lshl_add_u32 v3, s59, 6, v2
	v_cmp_lt_i32_e32 vcc, -1, v3
	v_mov_b32_e32 v3, 0
	v_mov_b32_e32 v4, 0
	s_and_saveexec_b64 s[6:7], vcc
	s_cbranch_execz .LBB0_670
	v_mov_b32_e32 v3, v252
	v_mov_b32_e32 v4, v253
	s_mov_b32 s8, 0x41a00000
	v_add_f32_e32 v4, v81, v4
	v_cmp_nlt_f32_e32 vcc, s8, v4
	s_and_saveexec_b64 s[8:9], vcc
	s_cbranch_execz .LBB0_669
	v_mul_f32_e32 v4, 0x3fb8aa3b, v4
	v_exp_f32_e32 v18, v4
	s_mov_b32 s59, 0x3f2aaaab
	v_add_f32_e32 v6, 1.0, v18
	v_frexp_mant_f32_e32 v8, v6
	v_cvt_f64_f32_e32 v[4:5], v6
	v_frexp_exp_i32_f64_e32 v4, v[4:5]
	v_cmp_gt_f32_e32 vcc, s59, v8
	v_add_f32_e32 v7, -1.0, v6
	v_sub_f32_e32 v9, v7, v6
	v_subbrev_co_u32_e32 v12, vcc, 0, v4, vcc
	v_sub_u32_e32 v4, 0, v12
	v_sub_f32_e32 v7, v18, v7
	v_add_f32_e32 v9, 1.0, v9
	v_ldexp_f32 v5, v6, v4
	v_add_f32_e32 v7, v7, v9
	v_add_f32_e32 v6, -1.0, v5
	v_add_f32_e32 v8, 1.0, v5
	v_ldexp_f32 v4, v7, v4
	v_add_f32_e32 v7, 1.0, v6
	v_add_f32_e32 v9, -1.0, v8
	v_sub_f32_e32 v7, v5, v7
	v_sub_f32_e32 v5, v5, v9
	v_add_f32_e32 v7, v4, v7
	v_add_f32_e32 v4, v4, v5
	v_add_f32_e32 v13, v8, v4
	v_rcp_f32_e32 v15, v13
	v_sub_f32_e32 v5, v13, v8
	v_sub_f32_e32 v14, v4, v5
	v_add_f32_e32 v5, v6, v7
	v_mul_f32_e32 v17, v5, v15
	v_sub_f32_e32 v4, v5, v6
	v_mul_f32_e32 v6, v13, v17
	v_fma_f32 v8, v17, v13, -v6
	v_fmac_f32_e32 v8, v17, v14
	v_sub_f32_e32 v16, v7, v4
	v_add_f32_e32 v4, v6, v8
	v_sub_f32_e32 v7, v5, v4
	v_pk_add_f32 v[10:11], v[4:5], v[6:7] neg_lo:[0,1] neg_hi:[0,1]
	v_mov_b32_e32 v9, v4
	v_pk_add_f32 v[4:5], v[10:11], v[8:9] neg_lo:[0,1] neg_hi:[0,1]
	s_mov_b32 s59, 0x3f317218
	v_add_f32_e32 v5, v16, v5
	v_add_f32_e32 v4, v4, v5
	v_add_f32_e32 v5, v7, v4
	v_mul_f32_e32 v16, v15, v5
	v_mul_f32_e32 v6, v13, v16
	v_fma_f32 v8, v16, v13, -v6
	v_fmac_f32_e32 v8, v16, v14
	v_sub_f32_e32 v7, v7, v5
	v_add_f32_e32 v13, v4, v7
	v_add_f32_e32 v4, v6, v8
	v_sub_f32_e32 v7, v5, v4
	v_pk_add_f32 v[10:11], v[4:5], v[6:7] neg_lo:[0,1] neg_hi:[0,1]
	v_mov_b32_e32 v9, v4
	v_pk_add_f32 v[4:5], v[10:11], v[8:9] neg_lo:[0,1] neg_hi:[0,1]
	s_nop 0
	v_add_f32_e32 v5, v13, v5
	v_add_f32_e32 v4, v4, v5
	v_add_f32_e32 v5, v17, v16
	v_add_f32_e32 v4, v7, v4
	v_sub_f32_e32 v6, v5, v17
	v_mul_f32_e32 v4, v15, v4
	v_sub_f32_e32 v6, v16, v6
	v_add_f32_e32 v6, v6, v4
	v_add_f32_e32 v8, v5, v6
	v_mul_f32_e32 v9, v8, v8
	v_fmamk_f32 v4, v9, 0x3e9b6dac, v107
	v_fmaak_f32 v81, v9, v4, 0x3f2aaada
	v_cvt_f32_i32_e32 v4, v12
	v_sub_f32_e32 v5, v8, v5
	v_sub_f32_e32 v5, v6, v5
	v_ldexp_f32 v10, v5, 1
	v_mul_f32_e32 v5, v8, v9
	v_ldexp_f32 v7, v8, 1
	v_pk_mul_f32 v[8:9], v[4:5], v[80:81]
	s_nop 0
	v_fma_f32 v6, v4, s59, -v8
	v_fmac_f32_e32 v6, 0xb102e308, v4
	v_pk_add_f32 v[4:5], v[8:9], v[6:7]
	s_mov_b32 s59, 0x7f800000
	v_sub_f32_e32 v7, v5, v7
	v_sub_f32_e32 v7, v9, v7
	v_add_f32_e32 v11, v10, v7
	v_mov_b32_e32 v10, v8
	v_pk_add_f32 v[8:9], v[4:5], v[8:9] neg_lo:[0,1] neg_hi:[0,1]
	v_pk_add_f32 v[12:13], v[4:5], v[10:11]
	v_mov_b32_e32 v7, v4
	v_mov_b32_e32 v9, v13
	v_pk_add_f32 v[14:15], v[6:7], v[8:9] neg_lo:[0,1] neg_hi:[0,1]
	v_pk_add_f32 v[6:7], v[6:7], v[8:9]
	v_mov_b32_e32 v10, v11
	v_pk_add_f32 v[8:9], v[6:7], v[4:5] op_sel:[1,0] op_sel_hi:[0,1] neg_lo:[0,1] neg_hi:[0,1]
	v_pk_add_f32 v[16:17], v[12:13], v[8:9] op_sel_hi:[1,0] neg_lo:[0,1] neg_hi:[0,1]
	v_mov_b32_e32 v12, v13
	v_mov_b32_e32 v13, v7
	v_pk_mov_b32 v[8:9], v[4:5], v[8:9] op_sel:[1,0]
	v_mov_b32_e32 v11, v4
	v_pk_add_f32 v[8:9], v[12:13], v[8:9] neg_lo:[0,1] neg_hi:[0,1]
	v_mov_b32_e32 v16, v14
	v_pk_add_f32 v[4:5], v[10:11], v[8:9] neg_lo:[0,1] neg_hi:[0,1]
	v_mov_b32_e32 v15, v7
	v_pk_add_f32 v[8:9], v[16:17], v[4:5]
	v_cmp_neq_f32_e32 vcc, s59, v18
	v_pk_add_f32 v[10:11], v[8:9], v[8:9] op_sel:[0,1] op_sel_hi:[1,0]
	s_mov_b32 s59, 0x33800000
	v_pk_add_f32 v[6:7], v[6:7], v[10:11] op_sel:[1,0] op_sel_hi:[0,1]
	v_mov_b32_e32 v9, v6
	v_pk_add_f32 v[12:13], v[8:9], v[14:15] neg_lo:[0,1] neg_hi:[0,1]
	v_mov_b32_e32 v5, v10
	v_sub_f32_e32 v7, v8, v12
	v_pk_add_f32 v[4:5], v[4:5], v[12:13] neg_lo:[0,1] neg_hi:[0,1]
	v_sub_f32_e32 v7, v14, v7
	v_add_f32_e32 v4, v4, v7
	v_add_f32_e32 v4, v4, v5
	v_add_f32_e32 v4, v6, v4
	v_cndmask_b32_e32 v4, v109, v4, vcc
	v_cmp_ngt_f32_e32 vcc, -1.0, v18
	s_nop 1
	v_cndmask_b32_e32 v4, v110, v4, vcc
	v_cmp_neq_f32_e32 vcc, -1.0, v18
	s_nop 1
	v_cndmask_b32_e32 v4, v111, v4, vcc
	v_cmp_lt_f32_e64 vcc, |v18|, s59
	s_nop 1
	v_cndmask_b32_e32 v4, v4, v18, vcc

; #define LAS __attribute__((address_space(3)))
; template <int SKIP>
; __device__ __forceinline__ void p2_chunk_prep_fast(Frame& F, const Args& a) {
;     ...
;         PREP_LOAD(raw, cu + 1 < u_hi ? cu + 1 : cu);
;         const float gl = gc[63];
;         if (!(SKIP & 2)) {
;             const int kind = w >> 2, ti = w & 3;
;             bf16x8_t af[4];
; #pragma unroll
;             for (int ks = 0; ks < 4; ++ks) af[ks] = *(const LAS bf16x8_t*)(L + L_KS + (16 * ti + fr) * QS_LD + (32 * ks + 8 * fq) * 2);
.LBB0_671:
	s_add_i32 s59, s84, 1
	s_cmp_ge_i32 s59, s16
	s_cselect_b64 s[8:9], -1, 0
	s_cmp_lt_i32 s59, s16
	s_cselect_b32 s6, s59, s84
	s_mul_hi_i32 s7, s6, 0x3e0f83e1
	s_ashr_i32 s85, s7, 3
	s_lshr_b32 s86, s7, 31
	s_add_i32 s85, s85, s86
	s_mul_i32 s87, s85, 33
	s_sub_i32 s87, s6, s87
	s_ashr_i32 s6, s85, 31
	s_lshr_b32 s6, s6, 28
	s_add_i32 s6, s85, s6
	s_and_b32 s6, s6, -16
	s_sub_i32 s6, s85, s6
	s_lshl_b32 s90, s6, 2
	v_mov_b32_e32 v249, s90
	global_load_dword v252, v249, s[46:47]
	global_load_dword v253, v249, s[48:49]
	s_lshl_b32 s85, s6, 7
	s_lshr_b32 s7, s7, 7
	s_add_i32 s85, s85, s58
	s_add_i32 s7, s7, s86
	v_or_b32_e32 v4, s85, v119
	s_lshl_b32 s85, s87, 6
	s_sub_i32 s86, s85, 51
	s_lshl_b32 s7, s7, 11
	v_lshl_add_u32 v3, v78, 3, s86
	s_add_i32 s7, s7, -16
	v_mov_b32_e32 v46, s7
	v_cmp_lt_i32_e32 vcc, 15, v3
	v_ashrrev_i32_e32 v5, 31, v4
	v_max_i32_e32 v6, 0, v3
	v_cndmask_b32_e32 v7, v112, v46, vcc
	v_cmp_lt_i32_e32 vcc, 14, v3
	v_lshl_add_u64 v[4:5], v[4:5], 1, s[18:19]
	v_add_u32_e32 v6, v7, v6
	v_max_i32_e32 v8, -1, v3
	v_cndmask_b32_e32 v9, v112, v46, vcc
	v_mad_i64_i32 v[6:7], s[86:87], v6, s55, v[4:5]
	v_add3_u32 v8, v8, v9, 1
	s_waitcnt lgkmcnt(0)
	s_barrier
	v_mad_i64_i32 v[8:9], s[86:87], v8, s55, v[4:5]
	global_load_dwordx4 v[30:33], v[6:7], off nt
	global_load_dwordx4 v[38:41], v[8:9], off nt
	v_or_b32_e32 v6, 2, v3
	v_cmp_lt_i32_e32 vcc, 15, v6
	v_max_i32_e32 v7, 0, v6
	v_max_i32_e32 v8, -3, v3
	v_cndmask_b32_e32 v6, v112, v46, vcc
	v_cmp_lt_i32_e32 vcc, 12, v3
	v_add_u32_e32 v6, v6, v7
	v_mad_i64_i32 v[6:7], s[86:87], v6, s55, v[4:5]
	v_cndmask_b32_e32 v9, v112, v46, vcc
	v_add3_u32 v8, v8, v9, 3
	v_cmp_lt_i32_e32 vcc, 11, v3
	v_mad_i64_i32 v[8:9], s[86:87], v8, s55, v[4:5]
	global_load_dwordx4 v[34:37], v[6:7], off nt
	global_load_dwordx4 v[42:45], v[8:9], off nt
	v_max_i32_e32 v6, -4, v3
	v_cndmask_b32_e32 v7, v112, v46, vcc
	v_cmp_lt_i32_e32 vcc, 10, v3
	v_add3_u32 v6, v6, v7, 4
	v_max_i32_e32 v8, -5, v3
	v_cndmask_b32_e32 v9, v112, v46, vcc
	v_mad_i64_i32 v[6:7], s[86:87], v6, s55, v[4:5]
	v_add3_u32 v8, v8, v9, 5
	v_cmp_lt_i32_e32 vcc, 9, v3
	v_mad_i64_i32 v[8:9], s[86:87], v8, s55, v[4:5]
	global_load_dwordx4 v[26:29], v[6:7], off nt
	global_load_dwordx4 v[22:25], v[8:9], off nt
	v_max_i32_e32 v6, -6, v3
	v_cndmask_b32_e32 v7, v112, v46, vcc
	v_cmp_lt_i32_e32 vcc, 8, v3
	v_add3_u32 v6, v6, v7, 6
	v_max_i32_e32 v8, -7, v3
	v_cndmask_b32_e32 v9, v112, v46, vcc
	v_mad_i64_i32 v[6:7], s[86:87], v6, s55, v[4:5]
	v_add3_u32 v8, v8, v9, 7
	v_cmp_lt_i32_e32 vcc, 7, v3
	v_mad_i64_i32 v[8:9], s[86:87], v8, s55, v[4:5]
	global_load_dwordx4 v[18:21], v[6:7], off nt
	global_load_dwordx4 v[14:17], v[8:9], off nt
	v_cndmask_b32_e32 v7, v112, v46, vcc
	v_cmp_lt_i32_e32 vcc, 6, v3
	v_max_i32_e32 v6, -8, v3
	v_max_i32_e32 v8, -9, v3
	v_cndmask_b32_e32 v9, v112, v46, vcc
	v_cmp_lt_i32_e32 vcc, 5, v3
	v_max_i32_e32 v47, -10, v3
	v_add_u32_e32 v2, s85, v2
	v_cndmask_b32_e32 v3, v112, v46, vcc
	v_add3_u32 v6, v6, v7, 8
	v_add3_u32 v8, v8, v9, 9
	v_add3_u32 v3, v47, v3, 10
	v_cmp_lt_i32_e32 vcc, 15, v2
	v_mad_i64_i32 v[6:7], s[86:87], v6, s55, v[4:5]
	v_mad_i64_i32 v[8:9], s[86:87], v8, s55, v[4:5]
	v_mad_i64_i32 v[4:5], s[86:87], v3, s55, v[4:5]
	v_max_i32_e32 v3, 0, v2
	v_cndmask_b32_e32 v2, v112, v46, vcc
	v_add_u32_e32 v2, v2, v3
	v_ashrrev_i32_e32 v3, 31, v2
	v_lshlrev_b64 v[2:3], 7, v[2:3]
	v_lshl_add_u64 v[2:3], s[20:21], 0, v[2:3]
	s_ashr_i32 s7, s6, 31
	global_load_dwordx4 v[10:13], v[6:7], off nt
	s_nop 0
	global_load_dwordx4 v[6:9], v[8:9], off nt
	v_lshl_add_u64 v[46:47], s[6:7], 2, v[2:3]
	global_load_dwordx4 v[2:5], v[4:5], off nt
	s_nop 0
	global_load_dword v106, v[46:47], off
	global_load_dword v81, v[46:47], off offset:64
	v_and_b32_e32 v66, -16, v117
	v_or_b32_e32 v47, s61, v83
	v_add_u32_e32 v72, 0, v66
	v_mov_b32_e32 v46, s62
	v_mad_u32_u24 v47, v47, s28, v72
	ds_read_b32 v71, v46
	ds_read_b128 v[58:61], v47 offset:17408
	ds_read_b128 v[54:57], v47 offset:17472
	ds_read_b128 v[50:53], v47 offset:17536
	ds_read_b128 v[46:49], v47 offset:17600
	v_lshlrev_b32_e32 v67, 2, v118
	v_add_u32_e32 v62, s61, v67
	s_ashr_i32 s85, s84, 31
	v_lshlrev_b32_e32 v63, 4, v62
	v_lshlrev_b32_e32 v62, 1, v62
	s_lshl_b64 s[86:87], s[84:85], 13
	v_readlane_b32 s6, v255, 34
	v_and_or_b32 v62, v62, 48, v83
	s_add_u32 s88, s6, s86
	v_readlane_b32 s6, v255, 35
	v_lshlrev_b32_e32 v69, 4, v118
	v_and_b32_e32 v63, 0xfffffe00, v63
	v_lshlrev_b32_e32 v62, 3, v62
	v_and_b32_e32 v68, 4, v67
	s_addc_u32 s89, s6, s87
	v_add_u32_e32 v75, s97, v69
	v_or3_b32 v62, v62, v63, v68
	s_mov_b64 s[6:7], -1
	v_readlane_b32 s100, v255, 19
	s_cmp_eq_u32 s100, 4
	s_cbranch_scc1 .Lst2_skip1
	s_cmp_eq_u32 s100, 0
	s_cbranch_scc1 .Lst2_do1
	s_and_b64 vcc, exec, s[38:39]
	s_cbranch_vccz .LBB0_675
